# speedup vs baseline: 1.0574x; 1.0157x over previous
.LBB0_132:
	v_mov_b32_e32 v0, 0x20000
	v_readlane_b32 s0, v254, 17
	v_add_u32_e32 v8, 0, v0
	ds_read2_b64 v[0:3], v8 offset1:1
	ds_read2_b64 v[4:7], v8 offset0:10 offset1:12
	ds_read_b64 v[8:9], v8 offset:224
	v_readlane_b32 s1, v254, 18
	s_and_b64 vcc, exec, s[0:1]
	s_mul_i32 s0, s98, 0x1800
	v_writelane_b32 v254, s0, 25
	s_waitcnt lgkmcnt(2)
	v_readfirstlane_b32 s8, v1
	v_readfirstlane_b32 s9, v0
	v_readfirstlane_b32 s10, v3
	v_readfirstlane_b32 s11, v2
	s_waitcnt lgkmcnt(1)
	v_readfirstlane_b32 s5, v5
	v_readfirstlane_b32 s4, v4
	v_readfirstlane_b32 s7, v7
	v_readfirstlane_b32 s6, v6
	s_waitcnt lgkmcnt(0)
	v_readfirstlane_b32 s3, v9
	v_readfirstlane_b32 s2, v8
	v_mov_b32_e32 v0, v208
	v_writelane_b32 v254, s1, 26
	s_mul_i32 s20, s98, 9
	s_cbranch_vccnz .LBB0_141
	s_mul_i32 s18, s98, 0x1800
	s_add_i32 s12, s20, 36
	s_add_i32 s13, s20, 0x48
	s_add_i32 s14, s20, 0x6c
	s_lshl_b32 s56, s98, 11
	v_add_u32_e32 v4, s18, v0
	s_cmp_lg_u32 s98, 0
	v_add_u32_e32 v8, 0x800, v4
	v_ashrrev_i32_e32 v1, 3, v0
	s_cselect_b64 s[0:1], -1, 0
	v_ashrrev_i32_e32 v9, 31, v8
	s_lshl_b32 s15, s98, 12
	v_and_b32_e32 v3, -8, v1
	v_lshlrev_b32_e32 v1, 3, v0
	v_lshl_add_u64 v[52:53], v[8:9], 2, s[6:7]
	v_subrev_u32_e32 v8, s15, v4
	v_and_b32_e32 v2, 0x1f8, v1
	v_ashrrev_i32_e32 v1, 31, v0
	v_ashrrev_i32_e32 v9, 31, v8
	s_ashr_i32 s19, s18, 31
	v_lshl_add_u64 v[56:57], v[8:9], 2, s[4:5]
	v_lshl_add_u64 v[8:9], v[0:1], 0, s[18:19]
	v_lshl_add_u64 v[58:59], v[8:9], 2, s[6:7]
	v_add_u32_e32 v8, 0xa00, v4
	v_ashrrev_i32_e32 v9, 31, v8
	v_lshl_add_u64 v[6:7], v[0:1], 2, s[2:3]
	s_mov_b64 s[16:17], 0xb800000
	v_lshl_add_u64 v[60:61], v[8:9], 2, s[6:7]
	v_lshl_add_u64 v[8:9], v[0:1], 0, s[56:57]
	v_lshl_add_u64 v[50:51], v[6:7], 0, s[16:17]
	s_mov_b64 s[16:17], 0xb802000
	v_lshl_add_u64 v[64:65], v[8:9], 2, s[4:5]
	v_add_u32_e32 v8, 0x400, v4
	v_lshl_add_u64 v[54:55], v[6:7], 0, s[16:17]
	s_mov_b32 s16, s18
	v_ashrrev_i32_e32 v9, 31, v8
	v_writelane_b32 v254, s16, 25
	v_lshl_add_u64 v[66:67], v[8:9], 2, s[6:7]
	v_subrev_u32_e32 v8, s15, v8
	v_ashrrev_i32_e32 v5, 31, v4
	v_writelane_b32 v254, s17, 26
	s_mov_b64 s[16:17], 0xb802800
	v_ashrrev_i32_e32 v9, 31, v8
	v_cmp_lt_i32_e32 vcc, v212, v211
	v_lshl_add_u64 v[48:49], v[4:5], 2, s[6:7]
	v_lshl_add_u64 v[62:63], v[6:7], 0, s[16:17]
	s_mov_b64 s[16:17], 0xb801000
	v_add_u32_e32 v10, 0xc00, v4
	v_lshl_add_u64 v[74:75], v[8:9], 2, s[4:5]
	v_add_u32_e32 v8, 0x600, v4
	v_add_u32_e32 v4, 0xe00, v4
	v_cndmask_b32_e32 v1, v210, v212, vcc
	v_cmp_lt_i32_e32 vcc, v213, v211
	v_lshl_add_u64 v[68:69], v[6:7], 0, s[16:17]
	v_ashrrev_i32_e32 v11, 31, v10
	s_mov_b64 s[16:17], 0xb803000
	v_ashrrev_i32_e32 v9, 31, v8
	v_ashrrev_i32_e32 v5, 31, v4
	v_lshlrev_b32_e32 v101, 2, v1
	v_cndmask_b32_e32 v1, v210, v213, vcc
	v_cmp_lt_i32_e32 vcc, v214, v211
	v_lshl_add_u64 v[70:71], v[10:11], 2, s[6:7]
	v_lshl_add_u64 v[72:73], v[6:7], 0, s[16:17]
	v_lshl_add_u64 v[76:77], v[8:9], 2, s[6:7]
	s_mov_b64 s[16:17], 0xb801800
	v_lshl_add_u64 v[80:81], v[4:5], 2, s[6:7]
	s_mov_b64 s[6:7], 0xb803800
	v_lshlrev_b32_e32 v102, 2, v1
	v_cndmask_b32_e32 v1, v210, v214, vcc
	v_cmp_lt_i32_e32 vcc, v215, v211
	v_lshlrev_b32_e32 v174, 1, v2
	v_lshl_add_u64 v[78:79], v[6:7], 0, s[16:17]
	v_lshl_add_u64 v[82:83], v[6:7], 0, s[6:7]
	v_subrev_u32_e32 v4, s15, v8
	v_lshlrev_b32_e32 v103, 2, v1
	v_cndmask_b32_e32 v1, v210, v215, vcc
	v_cmp_lt_i32_e32 vcc, v216, v211
	v_lshl_add_u64 v[6:7], s[2:3], 0, v[174:175]
	s_mov_b64 s[2:3], 0xfb68100
	v_ashrrev_i32_e32 v5, 31, v4
	v_lshlrev_b32_e32 v104, 2, v1
	v_cndmask_b32_e32 v1, v210, v216, vcc
	v_cmp_lt_i32_e32 vcc, v217, v211
	v_lshl_add_u64 v[86:87], v[6:7], 0, s[2:3]
	s_mov_b64 s[2:3], 0xbb68100
	v_lshl_add_u64 v[84:85], v[4:5], 2, s[4:5]
	v_lshl_add_u32 v97, v0, 2, 0
	v_or_b32_e32 v0, 0x400, v2
	v_or_b32_e32 v4, 0x600, v2
	v_lshlrev_b32_e32 v105, 2, v1
	v_cndmask_b32_e32 v1, v210, v217, vcc
	v_lshl_add_u64 v[88:89], v[6:7], 0, s[2:3]
	v_readlane_b32 s2, v254, 16
	v_lshl_add_u32 v100, v2, 2, 0
	v_lshlrev_b32_e32 v106, 2, v1
	v_add_u32_e32 v107, s2, v3
	v_lshlrev_b32_e32 v174, 2, v2
	v_lshlrev_b32_e32 v90, 2, v0
	v_lshlrev_b32_e32 v92, 2, v4
	v_readlane_b32 s4, v254, 15
	s_nop 1
	s_lshr_b32 s5, s4, 3
	s_and_b32 s2, s4, 7
	s_lshl_b32 s2, s2, 4
	s_and_b32 s4, s5, 15
	s_or_b32 s4, s4, s2
	s_lshr_b32 s5, s5, 4
	s_lshl_b32 s5, s5, 7
	s_or_b32 s4, s4, s5
	s_lshl_b32 s2, s4, 6
	v_add_u32_e32 v107, s2, v3
	s_branch .LBB0_135

.LBB0_180:
	s_waitcnt lgkmcnt(0)
	s_barrier
	s_cmpk_lt_i32 s99, 0x500
	s_cbranch_scc1 .Lsig_done
	s_waitcnt vmcnt(0)
	s_barrier
	v_cmp_eq_u32_e32 vcc, 0, v208
	s_and_b64 exec, exec, vcc
	s_cbranch_execz .Lsig_restore
	v_mov_b32_e32 v0, 0x200e8
	ds_read2_b32 v[0:1], v0 offset1:2
	v_readlane_b32 s100, v254, 2
	v_readlane_b32 s101, v254, 3
	v_readlane_b32 vcc_lo, v254, 28
	s_waitcnt lgkmcnt(0)
	v_and_b32_e32 v1, 7, v1
	v_lshlrev_b32_e32 v1, 2, v1
	s_cmpk_lt_i32 s99, 0x600
	s_cbranch_scc0 .Lsig_k6
	s_lshl_b32 vcc_lo, vcc_lo, 5
	s_addk_i32 vcc_lo, 0x3e40
	s_add_u32 s100, s100, vcc_lo
	s_addc_u32 s101, s101, 0
	s_nop 1
	global_atomic_add v1, v209, s[100:101]
	s_branch .Lsig_restore
.Lsig_k6:
	v_readfirstlane_b32 vcc_hi, v0
	s_nop 1
	s_cmp_eq_u32 vcc_hi, 0
	s_cbranch_scc1 .Lsig_k6_slow
	s_lshl_b32 vcc_lo, vcc_lo, 5
	s_addk_i32 vcc_lo, 0x3ec0
	s_add_u32 s100, s100, vcc_lo
	s_addc_u32 s101, s101, 0
	s_nop 1
	global_atomic_add v1, v209, s[100:101]
	s_branch .Lsig_restore

.LBB0_181:
	v_mov_b32_e32 v97, v208
	s_and_b32 s2, s99, 7
	v_ashrrev_i32_e32 v0, 31, v97
	v_lshrrev_b32_e32 v0, 26, v0
	v_add_u32_e32 v0, v97, v0
	v_ashrrev_i32_e32 v8, 6, v0
	v_bfe_i32 v0, v97, 27, 1
	v_lshlrev_b32_e32 v12, 4, v97
	v_lshrrev_b32_e32 v0, 22, v0
	v_add_u32_e32 v0, v12, v0
	v_and_b32_e32 v0, 0xfffffc00, v0
	v_sub_u32_e32 v0, v12, v0
	v_lshrrev_b32_e32 v1, 4, v0
	v_bitop3_b32 v0, v1, v0, 32 bitop3:0x6c
	v_ashrrev_i32_e32 v2, 31, v0
	v_lshrrev_b32_e32 v2, 26, v2
	v_add_u32_e32 v2, v0, v2
	v_ashrrev_i32_e32 v9, 6, v2
	v_and_b32_e32 v2, 0xc0, v2
	v_sub_u32_e32 v0, v0, v2
	v_lshlrev_b32_e32 v1, 3, v8
	v_lshlrev_b32_e32 v3, 5, v8
	v_ashrrev_i16_sdwa v0, v209, sext(v0) dst_sel:DWORD dst_unused:UNUSED_PAD src0_sel:DWORD src1_sel:BYTE_0
	v_and_b32_e32 v1, 0xffff0, v1
	v_and_b32_e32 v3, 32, v3
	v_bfe_i32 v10, v0, 0, 16
	v_add_u32_e32 v0, v3, v10
	v_add_lshl_u32 v1, v9, v1, 12
	s_ashr_i32 s4, s99, 3
	s_mulk_i32 s2, 0xd0
	v_lshl_add_u32 v174, v0, 1, v1
	v_add_u32_e32 v0, 0x2000, v12
	s_add_i32 s2, s2, s4
	v_ashrrev_i32_e32 v1, 31, v0
	s_mul_hi_i32 s4, s2, 0x4ec4ec4f
	v_lshrrev_b32_e32 v1, 22, v1
	s_lshr_b32 s5, s4, 31
	s_ashr_i32 s4, s4, 6
	v_add_u32_e32 v1, v0, v1
	s_add_i32 s4, s4, s5
	v_ashrrev_i32_e32 v11, 10, v1
	s_mul_i32 s5, s4, 0xd0
	v_mul_i32_i24_e32 v1, 0x400, v11
	s_sub_i32 s2, s2, s5
	v_sub_u32_e32 v0, v0, v1
	s_lshl_b32 s48, s2, 8
	v_lshrrev_b32_e32 v1, 4, v0
	s_lshl_b32 s4, s4, 11
	s_and_b32 s5, s48, 0x700
	v_bitop3_b32 v0, v1, v0, 32 bitop3:0x6c
	s_or_b32 s4, s5, s4
	s_lshr_b32 s5, s4, 1
	s_and_b32 s5, s5, 0xfffffc00
	s_bfe_u32 s6, s4, 0x1000a
	s_lshl_b32 s6, s6, 13
	s_and_b32 s4, s4, 0x300
	s_or_b32 s4, s4, s5
	s_or_b32 s4, s4, s6
	v_ashrrev_i32_e32 v2, 31, v0
	s_ashr_i32 s49, s2, 3
	v_lshrrev_b32_e32 v2, 26, v2
	s_ashr_i32 s5, s4, 31
	s_lshl_b32 s6, s49, 8
	v_add_u32_e32 v2, v0, v2
	s_lshl_b64 s[8:9], s[4:5], 12
	v_ashrrev_i32_e32 v13, 6, v2
	v_and_b32_e32 v2, 0xc0, v2
	s_add_u32 s8, s33, s8
	v_sub_u32_e32 v0, v0, v2
	s_addc_u32 s9, s58, s9
	s_ashr_i32 s7, s6, 31
	v_lshlrev_b32_e32 v1, 3, v11
	v_lshlrev_b32_e32 v3, 5, v11
	v_ashrrev_i16_sdwa v0, v209, sext(v0) dst_sel:DWORD dst_unused:UNUSED_PAD src0_sel:DWORD src1_sel:BYTE_0
	s_lshl_b64 s[10:11], s[6:7], 12
	s_waitcnt vmcnt(0)
	v_add_u32_e32 v144, s71, v12
	v_and_b32_e32 v1, 0xffff0, v1
	v_and_b32_e32 v3, 32, v3
	v_bfe_i32 v14, v0, 0, 16
	s_add_u32 s10, s59, s10
	v_readfirstlane_b32 s2, v144
	v_add_u32_e32 v146, 0x2000, v144
	v_add_u32_e32 v0, v3, v14
	v_add_lshl_u32 v1, v13, v1, 12
	s_addc_u32 s11, s76, s11
	s_mov_b32 m0, s2
	v_readfirstlane_b32 s2, v146
	v_add_u32_e32 v147, 0, v12
	v_lshl_add_u32 v130, v0, 1, v1
	global_load_lds_dwordx4 v174, s[10:11]
	s_mov_b32 m0, s2
	v_readfirstlane_b32 s2, v147
	v_add_u32_e32 v148, 0x2000, v147
	global_load_lds_dwordx4 v130, s[10:11]
	s_mov_b32 m0, s2
	v_readfirstlane_b32 s2, v148
	global_load_lds_dwordx4 v174, s[8:9]
	s_mov_b32 m0, s2
	v_readlane_b32 s2, v254, 20
	s_add_u32 s12, s10, 0x80000
	global_load_lds_dwordx4 v130, s[8:9]
	v_add_u32_e32 v149, s2, v12
	v_add_u32_e32 v150, 0x2000, v149
	v_readfirstlane_b32 s2, v149
	s_addc_u32 s13, s11, 0
	s_mov_b32 m0, s2
	v_readfirstlane_b32 s2, v150
	global_load_lds_dwordx4 v174, s[12:13]
	s_mov_b32 m0, s2
	v_add_u32_e32 v152, 0x4000, v147
	global_load_lds_dwordx4 v130, s[12:13]
	s_add_u32 s12, s8, 0x80000
	v_readfirstlane_b32 s2, v152
	v_add_u32_e32 v153, 0x6000, v147
	s_addc_u32 s13, s9, 0
	s_mov_b32 m0, s2
	v_readfirstlane_b32 s2, v153
	global_load_lds_dwordx4 v174, s[12:13]
	s_mov_b32 m0, s2
	v_ashrrev_i32_e32 v15, 8, v97
	global_load_lds_dwordx4 v130, s[12:13]
	v_mov_b32_e32 v131, v175
	v_lshl_add_u64 v[6:7], s[10:11], 0, v[174:175]
	v_lshl_add_u64 v[4:5], s[10:11], 0, v[130:131]
	v_lshl_add_u64 v[2:3], s[8:9], 0, v[174:175]
	v_lshl_add_u64 v[0:1], s[8:9], 0, v[130:131]
	v_cmp_eq_u32_e32 vcc, 1, v15
	s_and_saveexec_b64 s[12:13], vcc
	s_cbranch_execz .LBB0_183
	s_barrier

.LBB0_285:
	s_waitcnt vmcnt(0)
	s_barrier
	s_and_saveexec_b64 s[0:1], s[46:47]
	v_readlane_b32 s10, v254, 23
	s_mov_b64 s[12:13], 0x2000
	s_cbranch_execz .LBB0_322
	v_mov_b32_e32 v0, 0x200e8
	ds_read2_b32 v[0:1], v0 offset1:2
	ds_read_b32 v2, v0 offset:12
	s_waitcnt lgkmcnt(0)
	v_readfirstlane_b32 s2, v0
	s_nop 1
	s_cmp_eq_u32 s2, 0
	s_cbranch_scc1 .Lw1_slow
	v_readfirstlane_b32 s6, v2
	v_and_b32_e32 v1, 7, v1
	v_lshlrev_b32_e32 v2, 2, v1
	v_readlane_b32 s2, v254, 2
	v_readlane_b32 s3, v254, 3
	s_lshl_b32 s4, s98, 5
	s_addk_i32 s4, 0x3e40
	s_add_u32 s2, s2, s4
	s_addc_u32 s3, s3, 0
	s_mov_b32 s4, 0
	s_nop 2
.Lw1f_spin:
	global_load_dword v0, v2, s[2:3] sc1
	s_waitcnt vmcnt(0)
	v_readfirstlane_b32 s5, v0
	s_nop 1
	s_cmp_lt_u32 s5, s6
	s_cbranch_scc0 .Lw1_done
	s_add_i32 s4, s4, 1
	s_cmp_lt_u32 s4, 0x40000
	s_cbranch_scc0 .Lw1_done
	s_sleep 1
	s_branch .Lw1f_spin
.Lw1_slow:
	v_readlane_b32 s2, v254, 2
	v_readlane_b32 s3, v254, 3
	v_readlane_b32 s7, v254, 15
	s_lshl_b32 s4, s98, 3
	s_addk_i32 s4, 0x3e00
	s_add_u32 s8, s2, s4
	s_addc_u32 s9, s3, 0
	s_cmpk_lt_i32 s7, 0x80
	s_cbranch_scc1 .Lw1_global
	v_mov_b32_e32 v0, 0x200f0
	ds_read_b64 v[0:1], v0
	s_lshl_b32 s4, s98, 5
	s_addk_i32 s4, 0x3e40
	s_add_u32 s2, s2, s4
	s_addc_u32 s3, s3, 0
	s_mov_b32 s4, 0
	s_waitcnt lgkmcnt(0)
	v_readfirstlane_b32 s6, v1
	v_and_b32_e32 v0, 7, v0
	v_lshlrev_b32_e32 v2, 2, v0
	s_nop 1

.Lw1_again:
	s_add_i32 s4, s4, 1
	s_cmp_lt_u32 s4, 0x40000
	s_cbranch_scc0 .Lw1_done
	s_sleep 2
	s_branch .Lw1_spin
.Lw1_done:
	buffer_inv sc1
	s_waitcnt vmcnt(0)
.LBB0_322:
	s_or_b64 exec, exec, s[0:1]
	v_mov_b32_e32 v0, 0x20000
	s_barrier
	s_and_b32 s2, s98, 1
	v_add_u32_e32 v4, 0, v0
	ds_read_b64 v[6:7], v4 offset:216
	ds_read2_b64 v[0:3], v4 offset0:17 offset1:18
	s_mov_b32 s21, s57
	s_waitcnt lgkmcnt(0)
	v_readfirstlane_b32 s100, v6
	v_readfirstlane_b32 s101, v7
	s_nop 1
	s_sub_u32 s100, s100, 0xbb68100
	s_subb_u32 s101, s101, 0
	v_readfirstlane_b32 s0, v1
	s_nop 1
	v_writelane_b32 v254, s0, 43
	v_readfirstlane_b32 s0, v0
	v_readfirstlane_b32 s4, v3
	v_readfirstlane_b32 s5, v2
	ds_read2_b64 v[0:3], v4 offset0:24 offset1:28
	v_writelane_b32 v254, s0, 44
	s_lshl_b64 s[0:1], s[98:99], 5
	s_waitcnt lgkmcnt(0)
	v_readfirstlane_b32 s92, v2
	v_readfirstlane_b32 s93, v3
	s_add_u32 s0, s92, s0
	s_addc_u32 s1, s93, s1
	s_add_u32 s0, s0, 0xbb64080
	s_addc_u32 s1, s1, 0
	v_readlane_b32 s3, v254, 15
	s_nop 1
	s_and_b32 s3, s3, 7
	s_lshl_b32 s3, s3, 2
	s_add_u32 s0, s0, s3
	s_addc_u32 s1, s1, 0
	v_writelane_b32 v254, s0, 47
	s_bitcmp1_b32 s98, 0
	s_cselect_b64 s[96:97], -1, 0
	v_writelane_b32 v254, s1, 48
	s_add_u32 s0, s92, 0x20b68100
	v_writelane_b32 v254, s0, 39
	s_addc_u32 s0, s93, 0
	v_writelane_b32 v254, s0, 41
	s_add_u32 s0, s92, 0x9000000
	v_writelane_b32 v254, s0, 49
	s_addc_u32 s0, s93, 0
	v_writelane_b32 v254, s0, 50
	s_add_u32 s0, s92, 0xa000000
	v_writelane_b32 v254, s0, 51
	s_addc_u32 s0, s93, 0
	v_writelane_b32 v254, s0, 52
	s_add_u32 s0, s92, 0x22b68100
	v_writelane_b32 v254, s0, 42
	s_addc_u32 s0, s93, 0
	v_writelane_b32 v254, s0, 45
	s_add_u32 s0, s92, 0x27b68100
	v_writelane_b32 v254, s0, 53
	s_addc_u32 s0, s93, 0
	v_writelane_b32 v254, s0, 54
	s_add_u32 s0, s92, 0x24b68100
	v_writelane_b32 v254, s0, 46
	s_addc_u32 s0, s93, 0
	v_writelane_b32 v254, s0, 37
	s_and_b32 s0, s98, 2
	v_writelane_b32 v254, s0, 55
	s_add_u32 s0, s92, 0xb000000
	v_writelane_b32 v254, s0, 56
	s_addc_u32 s0, s93, 0
	v_writelane_b32 v254, s0, 57
	s_add_u32 s0, s92, 0xb400000
	v_writelane_b32 v254, s0, 58
	s_addc_u32 s0, s93, 0
	v_writelane_b32 v254, s0, 59
	s_add_u32 s0, s92, 0x26b68100
	v_writelane_b32 v254, s0, 60
	s_addc_u32 s0, s93, 0
	v_writelane_b32 v254, s0, 61
	s_add_u32 s0, s92, 0x27368100
	v_writelane_b32 v254, s0, 62
	s_addc_u32 s0, s93, 0
	v_writelane_b32 v254, s0, 63
	s_add_u32 s0, s92, 0x8800000
	v_writelane_b32 v254, s0, 31
	s_addc_u32 s0, s93, 0
	v_writelane_b32 v254, s0, 33
	s_add_u32 s0, s92, 0x8c00000
	v_writelane_b32 v254, s0, 34
	s_addc_u32 s0, s93, 0
	v_writelane_b32 v254, s0, 30
	s_lshl_b32 s0, s20, 3
	v_writelane_b32 v254, s0, 35
	s_add_u32 s0, s100, 0xbb68100
	v_writelane_b32 v254, s0, 36
	s_addc_u32 s0, s101, 0
	v_writelane_b32 v255, s0, 0
	s_lshl_b32 s0, s2, 10
	s_cmp_eq_u32 s2, 0
	v_writelane_b32 v255, s0, 1
	s_cselect_b64 s[0:1], -1, 0
	v_writelane_b32 v255, s0, 2
	v_readfirstlane_b32 s7, v0
	v_readfirstlane_b32 s6, v1
	v_writelane_b32 v255, s1, 3
	s_and_b64 s[0:1], s[0:1], exec
	s_movk_i32 s0, 0x1600
	s_cselect_b32 s0, 0x600, s0
	s_add_u32 s48, s92, 0x13b68100
	s_addc_u32 s49, s93, 0
	v_writelane_b32 v255, s0, 4
	s_add_u32 s0, s92, 0x29b68100
	s_addc_u32 s1, s93, 0
	v_writelane_b32 v255, s0, 5
	s_lshl_b32 s56, s20, 8
	v_mov_b32_e32 v0, v208
	v_writelane_b32 v255, s1, 6
	s_lshl_b64 s[0:1], s[56:57], 2
	s_add_u32 s2, s92, s0
	s_addc_u32 s3, s93, s1
	s_add_u32 s2, s2, 0xbb67700
	v_writelane_b32 v255, s2, 7
	s_addc_u32 s2, s3, 0
	v_writelane_b32 v255, s2, 8
	s_lshl_b64 s[2:3], s[20:21], 2
	s_add_u32 s2, s92, s2
	s_addc_u32 s3, s93, s3
	s_add_u32 s2, s2, 0xbb64000
	s_addc_u32 s3, s3, 0
	s_cmp_lt_u32 s98, 2
	v_writelane_b32 v255, s2, 9
	s_cselect_b64 vcc, -1, 0
	s_add_u32 s0, s7, s0
	v_writelane_b32 v255, s3, 10
	s_addc_u32 s1, s6, s1
	v_writelane_b32 v255, s0, 11
	s_mov_b32 s2, s20
	s_nop 0
	v_writelane_b32 v255, s1, 12
	v_writelane_b32 v255, s2, 13
	s_mul_i32 s1, s20, 0x3000
	s_mul_hi_u32 s0, s20, 0x3000
	v_writelane_b32 v255, s3, 14
	s_add_u32 s2, s5, s1
	s_addc_u32 s3, s4, s0
	v_writelane_b32 v255, s2, 15
	v_cmp_eq_u32_e64 s[14:15], 0, v0
	v_mov_b32_e32 v0, 0x3ee34c56
	v_writelane_b32 v255, s3, 16
	v_writelane_b32 v255, s14, 17
	v_cndmask_b32_e32 v97, v0, v219, vcc
	s_nop 0
	v_writelane_b32 v255, s15, 18
	s_mov_b32 s0, 0
	s_nop 0
	v_writelane_b32 v255, s0, 40
	s_branch .LBB0_325

.LBB0_329:
	s_or_b64 exec, exec, s[0:1]
	v_mov_b32_e32 v0, s10
	s_waitcnt lgkmcnt(0)
	s_barrier
	ds_read_b32 v0, v0
	s_mov_b64 s[0:1], -1
	s_waitcnt lgkmcnt(0)
	v_readfirstlane_b32 s6, v0
	s_cmpk_lt_u32 s6, 0x80
	s_cbranch_scc1 .Ltq_ok
	s_movk_i32 s6, 0x400
	s_branch .Ltq_done
.Ltq_ok:
	v_readlane_b32 s2, v254, 15
	s_nop 1
	s_and_b32 s2, s2, 7
	s_lshl_b32 s2, s2, 5
	s_lshr_b32 s3, s6, 5
	s_lshl_b32 s3, s3, 8
	s_and_b32 s6, s6, 31
	s_or_b32 s6, s6, s2
	s_or_b32 s6, s6, s3
.Ltq_done:
	s_cmpk_gt_i32 s6, 0x3ff
	s_cbranch_scc1 .LBB0_324
	s_cmpk_lt_i32 s6, 0x100
	s_cbranch_scc1 .Lw2_skip
	v_readlane_b32 s2, v255, 40
	s_nop 1
	s_cmp_lg_u32 s2, 0
	s_cbranch_scc1 .Lw2_skip
	s_and_saveexec_b64 vcc, s[14:15]
	s_cbranch_execz .Lw2_join
	v_mov_b32_e32 v0, 0x200e8
	ds_read2_b32 v[0:1], v0 offset1:2
	v_readlane_b32 s2, v254, 2
	v_readlane_b32 s3, v254, 3
	v_readlane_b32 s4, v254, 28
	s_waitcnt lgkmcnt(0)
	v_readfirstlane_b32 s5, v0
	s_nop 1
	s_cmp_eq_u32 s5, 0
	s_cbranch_scc1 .Lw2_slowaddr
	v_and_b32_e32 v1, 7, v1
	v_lshlrev_b32_e32 v1, 2, v1
	v_mov_b32_e32 v2, 16
	s_lshl_b32 s4, s4, 5
	s_addk_i32 s4, 0x3ec0
	s_branch .Lw2_addr
.Lw2_slowaddr:
	v_mov_b32_e32 v1, 0
	v_mov_b32_e32 v2, 0x80
	s_lshl_b32 s4, s4, 3
	s_addk_i32 s4, 0x3e04
.Lw2_addr:
	s_add_u32 s2, s2, s4
	s_addc_u32 s3, s3, 0
	s_mov_b32 s4, 0
	s_nop 2
.Lw2_spin:
	global_load_dword v0, v1, s[2:3] sc1
	s_waitcnt vmcnt(0)
	v_sub_u32_e32 v0, v0, v2
	s_nop 1
	v_readfirstlane_b32 s5, v0
	s_nop 1
	s_cmp_lt_i32 s5, 0
	s_cbranch_scc0 .Lw2_done
	s_add_i32 s4, s4, 1
	s_cmp_lt_u32 s4, 0x40000
	s_cbranch_scc0 .Lw2_done
	s_sleep 1
	s_branch .Lw2_spin
.Lw2_done:
	buffer_inv sc1
	s_waitcnt vmcnt(0)
.Lw2_join:
	s_or_b64 exec, exec, vcc
	s_barrier
	s_mov_b32 s2, 1
	s_nop 0
	v_writelane_b32 v255, s2, 40

.LBB0_506:
	s_waitcnt vmcnt(0)
	v_readlane_b32 s46, v254, 0
	v_readlane_b32 s47, v254, 1
	s_waitcnt vmcnt(63) expcnt(7) lgkmcnt(15)
	s_barrier
	s_and_saveexec_b64 s[0:1], s[46:47]
	v_readlane_b32 s49, v254, 4
	v_readlane_b32 s30, v254, 24
	s_mov_b32 s31, 0xc000
	s_mov_b32 s33, 0xe000
	s_mov_b32 s34, 0xf000
	s_cbranch_execz .LBB0_543
	s_cmp_eq_u32 s98, 3
	s_cbranch_scc1 .Lslow_C
	v_mov_b32_e32 v0, 0x200e8
	ds_read2_b32 v[0:1], v0 offset1:2
	s_waitcnt lgkmcnt(0)
	v_readfirstlane_b32 s2, v0
	s_cmp_eq_u32 s2, 0
	s_cbranch_scc1 .Lslow_C
	v_readlane_b32 s2, v254, 2
	v_readlane_b32 s3, v254, 3
	v_and_b32_e32 v1, 7, v1
	v_lshlrev_b32_e32 v1, 8, v1
	s_add_u32 s2, s2, 0x480
	s_addc_u32 s3, s3, 0
	s_nop 4
	global_atomic_add v0, v1, v209, s[2:3] sc0
	s_waitcnt vmcnt(0)
	v_or_b32_e32 v0, 31, v0
	v_add_u32_e32 v0, 1, v0
	s_mov_b32 s5, 0
	s_nop 0
	v_readfirstlane_b32 s4, v0

.LBB0_546:
	v_mov_b32_e32 v97, v208
	s_lshl_b32 s5, s27, 6
	v_ashrrev_i32_e32 v0, 31, v97
	v_lshrrev_b32_e32 v0, 26, v0
	v_add_u32_e32 v0, v97, v0
	v_ashrrev_i32_e32 v8, 6, v0
	v_bfe_i32 v0, v97, 27, 1
	v_lshlrev_b32_e32 v12, 4, v97
	v_lshrrev_b32_e32 v0, 22, v0
	v_add_u32_e32 v0, v12, v0
	v_and_b32_e32 v0, 0xfffffc00, v0
	v_sub_u32_e32 v0, v12, v0
	v_lshrrev_b32_e32 v1, 4, v0
	v_bitop3_b32 v0, v1, v0, 32 bitop3:0x6c
	v_ashrrev_i32_e32 v2, 31, v0
	v_lshrrev_b32_e32 v2, 26, v2
	v_add_u32_e32 v2, v0, v2
	v_ashrrev_i32_e32 v9, 6, v2
	v_and_b32_e32 v2, 0xc0, v2
	v_sub_u32_e32 v0, v0, v2
	v_lshlrev_b32_e32 v1, 3, v8
	v_lshlrev_b32_e32 v3, 5, v8
	v_ashrrev_i16_sdwa v0, v209, sext(v0) dst_sel:DWORD dst_unused:UNUSED_PAD src0_sel:DWORD src1_sel:BYTE_0
	v_and_b32_e32 v1, 0xffff0, v1
	v_and_b32_e32 v3, 32, v3
	v_bfe_i32 v10, v0, 0, 16
	v_add_u32_e32 v0, v3, v10
	v_add_lshl_u32 v1, v9, v1, 12
	s_ashr_i32 s4, s27, 3
	s_and_b32 s5, s5, 0x1c0
	v_lshl_add_u32 v174, v0, 1, v1
	v_add_u32_e32 v0, 0x2000, v12
	s_add_i32 s4, s5, s4
	v_ashrrev_i32_e32 v1, 31, v0
	s_ashr_i32 s5, s4, 31
	v_lshrrev_b32_e32 v1, 22, v1
	s_lshr_b32 s5, s5, 26
	v_add_u32_e32 v1, v0, v1
	s_add_i32 s5, s4, s5
	v_ashrrev_i32_e32 v11, 10, v1
	s_and_b32 s8, s5, 0xffffffc0
	v_mul_i32_i24_e32 v1, 0x400, v11
	s_sub_i32 s4, s4, s8
	v_sub_u32_e32 v0, v0, v1
	s_lshl_b32 s5, s5, 5
	s_lshl_b32 s8, s4, 8
	v_lshrrev_b32_e32 v1, 4, v0
	s_and_b32 s5, s5, 0xfffff800
	s_and_b32 s8, s8, 0x700
	v_bitop3_b32 v0, v1, v0, 32 bitop3:0x6c
	s_or_b32 s8, s8, s5
	s_lshr_b32 s5, s8, 1
	s_and_b32 s5, s5, 0xfffffc00
	s_bfe_u32 s9, s8, 0x1000a
	s_lshl_b32 s9, s9, 13
	s_and_b32 s8, s8, 0x300
	s_or_b32 s8, s8, s5
	s_or_b32 s8, s8, s9
	v_ashrrev_i32_e32 v2, 31, v0
	s_lshl_b32 s4, s4, 5
	v_lshrrev_b32_e32 v2, 26, v2
	s_ashr_i32 s9, s8, 31
	s_and_b32 s4, s4, 0xffffff00
	v_add_u32_e32 v2, v0, v2
	s_lshl_b64 s[10:11], s[8:9], 12
	v_ashrrev_i32_e32 v13, 6, v2
	v_and_b32_e32 v2, 0xc0, v2
	s_add_u32 s10, s18, s10
	v_sub_u32_e32 v0, v0, v2
	s_addc_u32 s11, s19, s11
	s_ashr_i32 s5, s4, 31
	v_lshlrev_b32_e32 v1, 3, v11
	v_lshlrev_b32_e32 v3, 5, v11
	v_ashrrev_i16_sdwa v0, v209, sext(v0) dst_sel:DWORD dst_unused:UNUSED_PAD src0_sel:DWORD src1_sel:BYTE_0
	s_lshl_b64 s[12:13], s[4:5], 12
	s_waitcnt vmcnt(0)
	v_add_u32_e32 v144, s71, v12
	v_and_b32_e32 v1, 0xffff0, v1
	v_and_b32_e32 v3, 32, v3
	v_bfe_i32 v14, v0, 0, 16
	s_add_u32 s12, s20, s12
	v_readfirstlane_b32 s9, v144
	v_add_u32_e32 v146, 0x2000, v144
	v_add_u32_e32 v0, v3, v14
	v_add_lshl_u32 v1, v13, v1, 12
	s_addc_u32 s13, s21, s13
	s_mov_b32 m0, s9
	v_readfirstlane_b32 s9, v146
	v_add_u32_e32 v147, 0, v12
	v_lshl_add_u32 v130, v0, 1, v1
	global_load_lds_dwordx4 v174, s[12:13]
	s_mov_b32 m0, s9
	v_readfirstlane_b32 s9, v147
	v_add_u32_e32 v148, 0x2000, v147
	global_load_lds_dwordx4 v130, s[12:13]
	s_mov_b32 m0, s9
	v_readfirstlane_b32 s9, v148
	global_load_lds_dwordx4 v174, s[10:11]
	s_mov_b32 m0, s9
	v_readlane_b32 s9, v254, 20
	s_add_u32 s14, s12, 0x80000
	global_load_lds_dwordx4 v130, s[10:11]
	v_add_u32_e32 v149, s9, v12
	v_add_u32_e32 v150, 0x2000, v149
	v_readfirstlane_b32 s9, v149
	s_addc_u32 s15, s13, 0
	s_mov_b32 m0, s9
	v_readfirstlane_b32 s9, v150
	global_load_lds_dwordx4 v174, s[14:15]
	s_mov_b32 m0, s9
	v_add_u32_e32 v152, 0x4000, v147
	global_load_lds_dwordx4 v130, s[14:15]
	s_add_u32 s14, s10, 0x80000
	v_readfirstlane_b32 s9, v152
	v_add_u32_e32 v153, 0x6000, v147
	s_addc_u32 s15, s11, 0
	s_mov_b32 m0, s9
	v_readfirstlane_b32 s9, v153
	global_load_lds_dwordx4 v174, s[14:15]
	s_mov_b32 m0, s9
	v_ashrrev_i32_e32 v15, 8, v97
	global_load_lds_dwordx4 v130, s[14:15]
	v_mov_b32_e32 v131, v175
	v_lshl_add_u64 v[6:7], s[12:13], 0, v[174:175]
	v_lshl_add_u64 v[4:5], s[12:13], 0, v[130:131]
	v_lshl_add_u64 v[2:3], s[10:11], 0, v[174:175]
	v_lshl_add_u64 v[0:1], s[10:11], 0, v[130:131]
	v_cmp_eq_u32_e32 vcc, 1, v15
	s_and_saveexec_b64 s[14:15], vcc
	s_cbranch_execz .LBB0_548
	s_barrier
